# c1 + first grid barrier uses the XCD barrier + forget-weight LDS staging loads issued together
# speedup vs baseline: 1.0066x; 1.0066x over previous
; DEVI void norm_phase(const float* __restrict__ x, const float* __restrict__ gain, bf16_t* __restrict__ out,
;                      const float* wf_src, const float* bf_src, float* logf, char* lds, int wv) {
;     ...
;     float* wf = (float*)lds;
;     if (wf_src) {
;         for (int e = tid; e < 8192; e += 512) { const int k = e >> 3, h = e & 7; wf[h * 1024 + k] = wf_src[(size_t)k * NIN + 3072 + h]; }
;         __syncthreads();
.LBB0_462:
	s_load_dwordx2 s[6:7], s[30:31], 0x28
	s_load_dwordx2 s[4:5], s[30:31], 0x38
	s_cmp_lg_u64 s[10:11], 0
	v_mov_b32_e32 v2, v217
	s_cselect_b64 s[78:79], -1, 0
	s_cmp_eq_u64 s[10:11], 0
	s_cbranch_scc1 .LBB0_476
	s_movk_i32 s10, 0x2000
	v_cmp_gt_i32_e32 vcc, s10, v2
	s_and_saveexec_b64 s[10:11], vcc
	s_cbranch_execz .LBB0_475
	v_and_b32_e32 v6, 7, v2
	v_lshrrev_b32_e32 v3, 3, v2
	v_mul_u32_u24_e32 v4, 0x7020, v3
	v_lshl_add_u32 v4, v6, 2, v4
	v_add_u32_e32 v4, 0x3000, v4
	v_lshlrev_b32_e32 v5, 12, v6
	v_lshl_add_u32 v5, v3, 2, v5
	s_mov_b64 s[98:99], s[8:9]
	global_load_dword v8, v4, s[98:99]
	s_add_u32 s98, s98, 0x1c0800
	s_addc_u32 s99, s99, 0
	global_load_dword v9, v4, s[98:99]
	s_add_u32 s98, s98, 0x1c0800
	s_addc_u32 s99, s99, 0
	global_load_dword v10, v4, s[98:99]
	s_add_u32 s98, s98, 0x1c0800
	s_addc_u32 s99, s99, 0
	global_load_dword v11, v4, s[98:99]
	s_add_u32 s98, s98, 0x1c0800
	s_addc_u32 s99, s99, 0
	global_load_dword v12, v4, s[98:99]
	s_add_u32 s98, s98, 0x1c0800
	s_addc_u32 s99, s99, 0
	global_load_dword v13, v4, s[98:99]
	s_add_u32 s98, s98, 0x1c0800
	s_addc_u32 s99, s99, 0
	global_load_dword v14, v4, s[98:99]
	s_add_u32 s98, s98, 0x1c0800
	s_addc_u32 s99, s99, 0
	global_load_dword v15, v4, s[98:99]
	s_add_u32 s98, s98, 0x1c0800
	s_addc_u32 s99, s99, 0
	global_load_dword v16, v4, s[98:99]
	s_add_u32 s98, s98, 0x1c0800
	s_addc_u32 s99, s99, 0
	global_load_dword v17, v4, s[98:99]
	s_add_u32 s98, s98, 0x1c0800
	s_addc_u32 s99, s99, 0
	global_load_dword v18, v4, s[98:99]
	s_add_u32 s98, s98, 0x1c0800
	s_addc_u32 s99, s99, 0
	global_load_dword v19, v4, s[98:99]
	s_add_u32 s98, s98, 0x1c0800
	s_addc_u32 s99, s99, 0
	global_load_dword v20, v4, s[98:99]
	s_add_u32 s98, s98, 0x1c0800
	s_addc_u32 s99, s99, 0
	global_load_dword v21, v4, s[98:99]
	s_add_u32 s98, s98, 0x1c0800
	s_addc_u32 s99, s99, 0
	global_load_dword v22, v4, s[98:99]
	s_add_u32 s98, s98, 0x1c0800
	s_addc_u32 s99, s99, 0
	global_load_dword v23, v4, s[98:99]
	s_waitcnt vmcnt(0)
	ds_write_b32 v5, v8
	ds_write_b32 v5, v9 offset:256
	ds_write_b32 v5, v10 offset:512
	ds_write_b32 v5, v11 offset:768
	ds_write_b32 v5, v12 offset:1024
	ds_write_b32 v5, v13 offset:1280
	ds_write_b32 v5, v14 offset:1536
	ds_write_b32 v5, v15 offset:1792
	ds_write_b32 v5, v16 offset:2048
	ds_write_b32 v5, v17 offset:2304
	ds_write_b32 v5, v18 offset:2560
	ds_write_b32 v5, v19 offset:2816
	ds_write_b32 v5, v20 offset:3072
	ds_write_b32 v5, v21 offset:3328
	ds_write_b32 v5, v22 offset:3584
	ds_write_b32 v5, v23 offset:3840

; DEVI int ltid(int wv) { int t = (wv << 6) | (int)__builtin_amdgcn_mbcnt_hi(~0u, __builtin_amdgcn_mbcnt_lo(~0u, 0u)); asm volatile("" : "+v"(t)); return t; }
; DEVI unsigned xb_ld(unsigned* p)              { return __hip_atomic_load(p, __ATOMIC_RELAXED, __HIP_MEMORY_SCOPE_AGENT); }
; #define GBAR() do { XcdBarrier xb_; xb_.bar = (unsigned*)(ws + WS_BAR); xb_.x = xb_xcc_id(); xb_.st = (volatile LAS unsigned*)(lds + LDS_BAR); xcd_barrier(xb_, wv); } while (0)
; DEVI void xcd_barrier_complete(unsigned* bar, unsigned x, unsigned& nloc, unsigned& nx) {
;     const unsigned G = gridDim.x * gridDim.y * gridDim.z;
;     unsigned sum, cnt, mine, sp = 0u;
;     for (;;) {
;         sum = 0u; cnt = 0u; mine = 0u;
; #pragma unroll
;         for (unsigned j = 0; j < 16; ++j) { const unsigned c = xb_ld(&bar[XB_XCNT(j)]); sum += c; cnt += (c > 0u) ? 1u : 0u; mine = (j == x) ? c : mine; }
;         if (sum == G) break;
;         __builtin_amdgcn_s_sleep(1);
;         if ((++sp & 255u) == 0u) { if (xb_ld(&bar[XB_TMO])) break; if (sp > XB_SPIN_CAP) { atomicAdd(&bar[XB_TMO], 1u); break; } }
;     }
;     nloc = mine > 0u ? mine : 1u; nx = cnt > 0u ? cnt : 1u;
; }
; DEVI void xcd_barrier(const XcdBarrier& b, int wv) {
;     asm volatile("s_waitcnt vmcnt(0)" ::: "memory");
;     __syncthreads();
;     if (ltid(wv) == 0) {
;         unsigned* bar = b.bar;
;         __builtin_amdgcn_s_waitcnt(0);
;         unsigned nloc = b.st[0], nx = b.st[1];
;         if (nloc == 0u) { xcd_barrier_complete(bar, b.x, nloc, nx); b.st[0] = nloc; b.st[1] = nx; }
; __global__ void __launch_bounds__(512, 2) fwd_mega(Args a) {
;     ...
;         if (ph + 1 < a.ph_hi) { if (ph == a.ph_lo) grid.sync(); else for (int sr_ = 0; sr_ < SYNC_REPS; ++sr_) GBAR(); }
.LBB0_549:
	s_load_dwordx2 s[34:35], s[0:1], 0xd0
	s_load_dwordx2 s[30:31], s[0:1], 0xc8
	s_add_i32 s4, s53, 1
	s_waitcnt lgkmcnt(0)
	s_cmp_ge_i32 s4, s35
	s_cbranch_scc1 .LBB0_10
	s_cmp_eq_u32 s53, s34
	s_mov_b64 s[4:5], -1
	s_getreg_b32 s4, hwreg(HW_REG_XCC_ID, 0, 4)
	s_waitcnt vmcnt(0)
	v_mov_b32_e32 v0, v217
	s_waitcnt vmcnt(0)
	s_barrier
	s_nop 0
	v_cmp_eq_u32_e32 vcc, 0, v0
	s_and_saveexec_b64 s[66:67], vcc
	s_cbranch_execz .LBB0_595
	s_add_u32 s68, s64, 0x21941200
	s_addc_u32 s69, s65, 0
	s_add_i32 s42, 0, 0x24000
	v_mov_b32_e32 v0, s42
	s_waitcnt vmcnt(0) expcnt(0) lgkmcnt(0)
	ds_read_b32 v2, v0
	v_readlane_b32 s5, v255, 12
	s_and_b32 s26, s4, 15
	s_waitcnt lgkmcnt(0)
	v_cmp_ne_u32_e32 vcc, 0, v2
	v_mov_b32_e32 v0, s5
	ds_read_b32 v0, v0
	s_cbranch_vccnz .LBB0_566
	s_add_u32 s4, s64, 0x21941400
	s_addc_u32 s5, s65, 0
	s_add_u32 s6, s64, 0x21941500
	s_addc_u32 s7, s65, 0
	s_add_u32 s8, s64, 0x21941600
	s_addc_u32 s9, s65, 0
	s_add_u32 s10, s64, 0x21941700
	s_addc_u32 s11, s65, 0
	s_add_u32 s12, s64, 0x21941800
	s_addc_u32 s13, s65, 0
	s_add_u32 s14, s64, 0x21941900
	s_addc_u32 s15, s65, 0
	s_add_u32 s16, s64, 0x21941a00
	s_addc_u32 s17, s65, 0
	s_add_u32 s18, s64, 0x21941b00
	s_addc_u32 s19, s65, 0
	s_add_u32 s20, s64, 0x21941c00
	s_addc_u32 s21, s65, 0
	s_add_u32 s22, s64, 0x21941d00
	s_addc_u32 s23, s65, 0
	s_add_u32 s24, s64, 0x21941e00
	s_addc_u32 s25, s65, 0
	s_add_u32 s28, s64, 0x21941f00
	s_addc_u32 s29, s65, 0
	s_add_u32 s30, s64, 0x21942000
	s_addc_u32 s31, s65, 0
	s_add_u32 s34, s64, 0x21942100
	s_addc_u32 s35, s65, 0
	s_add_u32 s36, s64, 0x21942200
	s_addc_u32 s37, s65, 0
	s_add_u32 s70, s64, 0x21942300
	s_addc_u32 s71, s65, 0
	s_mov_b32 s46, 1
	s_mov_b64 s[72:73], 0
	s_branch .LBB0_556
